# counted waits + streamed slab reduction in norm phases; nt on converted-weight stores, SGU V loads and other dead-after-read loads (grid barrier code as baseline)
# baseline (speedup 1.0000x reference)
.LBB0_168:
	s_lshl_b32 s13, s13, 6
	s_add_i32 s4, s13, 0x500
	s_mov_b32 s5, 0
	s_lshl_b64 s[0:1], s[4:5], 2
	s_add_u32 s0, s38, s0
	s_addc_u32 s1, s39, s1
	v_mov_b32_e32 v1, 1
	v_mov_b64_e32 v[6:7], s[0:1]
	flat_atomic_add v1, v[6:7], v1 sc0
	v_cvt_f32_u32_e32 v3, v4
	v_sub_u32_e32 v5, 0, v4
	v_rcp_iflag_f32_e32 v3, v3
	s_nop 0
	v_mul_f32_e32 v3, 0x4f7ffffe, v3
	v_cvt_u32_f32_e32 v3, v3
	v_mul_lo_u32 v5, v5, v3
	v_mul_hi_u32 v5, v3, v5
	v_add_u32_e32 v3, v3, v5
	s_waitcnt vmcnt(0) lgkmcnt(0)
	v_mul_hi_u32 v3, v1, v3
	v_mul_lo_u32 v5, v3, v4
	v_add_u32_e32 v6, 1, v1
	v_sub_u32_e32 v1, v1, v5
	v_add_u32_e32 v7, 1, v3
	v_cmp_ge_u32_e32 vcc, v1, v4
	v_sub_u32_e32 v5, v1, v4
	s_nop 0
	v_cndmask_b32_e32 v3, v3, v7, vcc
	v_cndmask_b32_e32 v1, v1, v5, vcc
	v_add_u32_e32 v5, 1, v3
	v_cmp_ge_u32_e32 vcc, v1, v4
	s_nop 1
	v_cndmask_b32_e32 v1, v3, v5, vcc
	v_mad_u64_u32 v[4:5], s[0:1], v4, v1, v[4:5]
	v_cmp_ne_u32_e32 vcc, v6, v4
	s_and_saveexec_b64 s[0:1], vcc
	s_xor_b64 s[2:3], exec, s[0:1]
	s_cbranch_execz .LBB0_181
	s_add_i32 s4, s13, 0x900
	s_lshl_b64 s[0:1], s[4:5], 2
	s_add_u32 s6, s38, s0
	s_addc_u32 s7, s39, s1
	v_mov_b64_e32 v[2:3], s[6:7]
	flat_load_dword v2, v[2:3] sc1
	s_waitcnt vmcnt(0) lgkmcnt(0)
	v_cmp_eq_u32_e32 vcc, v2, v1
	s_and_saveexec_b64 s[4:5], vcc
	s_cbranch_execz .LBB0_180
	s_mov_b32 s0, 1
	s_mov_b64 s[8:9], 0
	s_branch .LBB0_172

.LBB0_180:
	s_or_b64 exec, exec, s[4:5]
	s_waitcnt vmcnt(0) lgkmcnt(0)
	buffer_inv sc1
	s_waitcnt vmcnt(0)

.LBB0_544:
	s_lshl_b32 s26, s40, 6
	s_add_i32 s86, s26, 0x500
	s_lshl_b64 s[0:1], s[86:87], 2
	s_add_u32 s0, s38, s0
	s_addc_u32 s1, s39, s1
	v_mov_b64_e32 v[6:7], s[0:1]
	flat_atomic_add v5, v[6:7], v1 sc0
	v_cvt_f32_u32_e32 v3, v4
	v_sub_u32_e32 v6, 0, v4
	v_rcp_iflag_f32_e32 v3, v3
	s_nop 0
	v_mul_f32_e32 v3, 0x4f7ffffe, v3
	v_cvt_u32_f32_e32 v3, v3
	v_mul_lo_u32 v6, v6, v3
	v_mul_hi_u32 v6, v3, v6
	v_add_u32_e32 v3, v3, v6
	s_waitcnt vmcnt(0) lgkmcnt(0)
	v_mul_hi_u32 v3, v5, v3
	v_mul_lo_u32 v6, v3, v4
	v_sub_u32_e32 v6, v5, v6
	v_cmp_ge_u32_e32 vcc, v6, v4
	v_add_u32_e32 v7, 1, v3
	s_nop 0
	v_cndmask_b32_e32 v3, v3, v7, vcc
	v_sub_u32_e32 v7, v6, v4
	v_cndmask_b32_e32 v6, v6, v7, vcc
	v_cmp_ge_u32_e32 vcc, v6, v4
	v_add_u32_e32 v6, 1, v3
	s_nop 0
	v_cndmask_b32_e32 v3, v3, v6, vcc
	v_add_u32_e32 v6, 1, v5
	v_mad_u64_u32 v[4:5], s[0:1], v4, v3, v[4:5]
	v_cmp_ne_u32_e32 vcc, v6, v4
	s_and_saveexec_b64 s[0:1], vcc
	s_xor_b64 s[2:3], exec, s[0:1]
	s_cbranch_execz .LBB0_557
	s_add_i32 s86, s26, 0x900
	s_lshl_b64 s[0:1], s[86:87], 2
	s_add_u32 s6, s38, s0
	s_addc_u32 s7, s39, s1
	v_mov_b64_e32 v[4:5], s[6:7]
	flat_load_dword v2, v[4:5] sc1
	s_waitcnt vmcnt(0) lgkmcnt(0)
	v_cmp_eq_u32_e32 vcc, v2, v3
	s_and_saveexec_b64 s[4:5], vcc
	s_cbranch_execz .LBB0_556
	s_mov_b32 s0, 1
	s_mov_b64 s[8:9], 0
	s_branch .LBB0_548

.LBB0_594:
	s_lshl_b32 s24, s40, 6
	s_add_i32 s86, s24, 0x500
	s_lshl_b64 s[0:1], s[86:87], 2
	s_add_u32 s0, s38, s0
	s_addc_u32 s1, s39, s1
	v_mov_b64_e32 v[6:7], s[0:1]
	flat_atomic_add v5, v[6:7], v1 sc0
	v_cvt_f32_u32_e32 v3, v4
	v_sub_u32_e32 v6, 0, v4
	v_rcp_iflag_f32_e32 v3, v3
	s_nop 0
	v_mul_f32_e32 v3, 0x4f7ffffe, v3
	v_cvt_u32_f32_e32 v3, v3
	v_mul_lo_u32 v6, v6, v3
	v_mul_hi_u32 v6, v3, v6
	v_add_u32_e32 v3, v3, v6
	s_waitcnt vmcnt(0) lgkmcnt(0)
	v_mul_hi_u32 v3, v5, v3
	v_mul_lo_u32 v6, v3, v4
	v_sub_u32_e32 v6, v5, v6
	v_cmp_ge_u32_e32 vcc, v6, v4
	v_add_u32_e32 v7, 1, v3
	s_nop 0
	v_cndmask_b32_e32 v3, v3, v7, vcc
	v_sub_u32_e32 v7, v6, v4
	v_cndmask_b32_e32 v6, v6, v7, vcc
	v_cmp_ge_u32_e32 vcc, v6, v4
	v_add_u32_e32 v6, 1, v3
	s_nop 0
	v_cndmask_b32_e32 v3, v3, v6, vcc
	v_add_u32_e32 v6, 1, v5
	v_mad_u64_u32 v[4:5], s[0:1], v4, v3, v[4:5]
	v_cmp_ne_u32_e32 vcc, v6, v4
	s_and_saveexec_b64 s[0:1], vcc
	s_xor_b64 s[2:3], exec, s[0:1]
	s_cbranch_execz .LBB0_607
	s_add_i32 s86, s24, 0x900
	s_lshl_b64 s[0:1], s[86:87], 2
	s_add_u32 s6, s38, s0
	s_addc_u32 s7, s39, s1
	v_mov_b64_e32 v[4:5], s[6:7]
	flat_load_dword v2, v[4:5] sc1
	s_waitcnt vmcnt(0) lgkmcnt(0)
	v_cmp_eq_u32_e32 vcc, v2, v3
	s_and_saveexec_b64 s[4:5], vcc
	s_cbranch_execz .LBB0_606
	s_mov_b32 s0, 1
	s_mov_b64 s[8:9], 0
	s_branch .LBB0_598

.LBB0_734:
	s_lshl_b32 s26, s49, 6
	s_add_i32 s86, s26, 0x500
	s_lshl_b64 s[0:1], s[86:87], 2
	s_add_u32 s0, s38, s0
	s_addc_u32 s1, s39, s1
	v_mov_b64_e32 v[6:7], s[0:1]
	flat_atomic_add v5, v[6:7], v1 sc0
	v_cvt_f32_u32_e32 v3, v4
	v_sub_u32_e32 v6, 0, v4
	v_rcp_iflag_f32_e32 v3, v3
	s_nop 0
	v_mul_f32_e32 v3, 0x4f7ffffe, v3
	v_cvt_u32_f32_e32 v3, v3
	v_mul_lo_u32 v6, v6, v3
	v_mul_hi_u32 v6, v3, v6
	v_add_u32_e32 v3, v3, v6
	s_waitcnt vmcnt(0) lgkmcnt(0)
	v_mul_hi_u32 v3, v5, v3
	v_mul_lo_u32 v6, v3, v4
	v_sub_u32_e32 v6, v5, v6
	v_cmp_ge_u32_e32 vcc, v6, v4
	v_add_u32_e32 v7, 1, v3
	s_nop 0
	v_cndmask_b32_e32 v3, v3, v7, vcc
	v_sub_u32_e32 v7, v6, v4
	v_cndmask_b32_e32 v6, v6, v7, vcc
	v_cmp_ge_u32_e32 vcc, v6, v4
	v_add_u32_e32 v6, 1, v3
	s_nop 0
	v_cndmask_b32_e32 v3, v3, v6, vcc
	v_add_u32_e32 v6, 1, v5
	v_mad_u64_u32 v[4:5], s[0:1], v4, v3, v[4:5]
	v_cmp_ne_u32_e32 vcc, v6, v4
	s_and_saveexec_b64 s[0:1], vcc
	s_xor_b64 s[2:3], exec, s[0:1]
	s_cbranch_execz .LBB0_747
	s_add_i32 s86, s26, 0x900
	s_lshl_b64 s[0:1], s[86:87], 2
	s_add_u32 s6, s38, s0
	s_addc_u32 s7, s39, s1
	v_mov_b64_e32 v[4:5], s[6:7]
	flat_load_dword v2, v[4:5] sc1
	s_waitcnt vmcnt(0) lgkmcnt(0)
	v_cmp_eq_u32_e32 vcc, v2, v3
	s_and_saveexec_b64 s[4:5], vcc
	s_cbranch_execz .LBB0_746
	s_mov_b32 s0, 1
	s_mov_b64 s[8:9], 0
	s_branch .LBB0_738

.LBB0_923:
	s_lshl_b32 s28, s49, 6
	s_add_i32 s86, s28, 0x500
	s_lshl_b64 s[0:1], s[86:87], 2
	s_add_u32 s0, s2, s0
	s_addc_u32 s1, s3, s1
	v_mov_b64_e32 v[6:7], s[0:1]
	flat_atomic_add v5, v[6:7], v1 sc0
	v_cvt_f32_u32_e32 v3, v4
	v_sub_u32_e32 v6, 0, v4
	v_rcp_iflag_f32_e32 v3, v3
	s_nop 0
	v_mul_f32_e32 v3, 0x4f7ffffe, v3
	v_cvt_u32_f32_e32 v3, v3
	v_mul_lo_u32 v6, v6, v3
	v_mul_hi_u32 v6, v3, v6
	v_add_u32_e32 v3, v3, v6
	s_waitcnt vmcnt(0) lgkmcnt(0)
	v_mul_hi_u32 v3, v5, v3
	v_mul_lo_u32 v6, v3, v4
	v_sub_u32_e32 v6, v5, v6
	v_cmp_ge_u32_e32 vcc, v6, v4
	v_add_u32_e32 v7, 1, v3
	s_nop 0
	v_cndmask_b32_e32 v3, v3, v7, vcc
	v_sub_u32_e32 v7, v6, v4
	v_cndmask_b32_e32 v6, v6, v7, vcc
	v_cmp_ge_u32_e32 vcc, v6, v4
	v_add_u32_e32 v6, 1, v3
	s_nop 0
	v_cndmask_b32_e32 v3, v3, v6, vcc
	v_add_u32_e32 v6, 1, v5
	v_mad_u64_u32 v[4:5], s[0:1], v4, v3, v[4:5]
	v_cmp_ne_u32_e32 vcc, v6, v4
	s_and_saveexec_b64 s[0:1], vcc
	s_xor_b64 s[4:5], exec, s[0:1]
	s_cbranch_execz .LBB0_936
	s_add_i32 s86, s28, 0x900
	s_lshl_b64 s[0:1], s[86:87], 2
	s_add_u32 s8, s2, s0
	s_addc_u32 s9, s3, s1
	v_mov_b64_e32 v[4:5], s[8:9]
	flat_load_dword v2, v[4:5] sc1
	s_waitcnt vmcnt(0) lgkmcnt(0)
	v_cmp_eq_u32_e32 vcc, v2, v3
	s_and_saveexec_b64 s[6:7], vcc
	s_cbranch_execz .LBB0_935
	s_mov_b32 s0, 1
	s_mov_b64 s[10:11], 0
	s_branch .LBB0_927

.LBB0_935:
	s_or_b64 exec, exec, s[6:7]
	s_waitcnt vmcnt(0) lgkmcnt(0)
	buffer_inv sc1
	s_waitcnt vmcnt(0)

.LBB0_1012:
	s_lshl_b32 s30, s49, 6
	s_add_i32 s86, s30, 0x500
	s_lshl_b64 s[0:1], s[86:87], 2
	s_add_u32 s0, s4, s0
	s_addc_u32 s1, s5, s1
	v_mov_b64_e32 v[6:7], s[0:1]
	flat_atomic_add v5, v[6:7], v1 sc0
	v_cvt_f32_u32_e32 v3, v4
	v_sub_u32_e32 v6, 0, v4
	v_rcp_iflag_f32_e32 v3, v3
	s_nop 0
	v_mul_f32_e32 v3, 0x4f7ffffe, v3
	v_cvt_u32_f32_e32 v3, v3
	v_mul_lo_u32 v6, v6, v3
	v_mul_hi_u32 v6, v3, v6
	v_add_u32_e32 v3, v3, v6
	s_waitcnt vmcnt(0) lgkmcnt(0)
	v_mul_hi_u32 v3, v5, v3
	v_mul_lo_u32 v6, v3, v4
	v_sub_u32_e32 v6, v5, v6
	v_cmp_ge_u32_e32 vcc, v6, v4
	v_add_u32_e32 v7, 1, v3
	s_nop 0
	v_cndmask_b32_e32 v3, v3, v7, vcc
	v_sub_u32_e32 v7, v6, v4
	v_cndmask_b32_e32 v6, v6, v7, vcc
	v_cmp_ge_u32_e32 vcc, v6, v4
	v_add_u32_e32 v6, 1, v3
	s_nop 0
	v_cndmask_b32_e32 v3, v3, v6, vcc
	v_add_u32_e32 v6, 1, v5
	v_mad_u64_u32 v[4:5], s[0:1], v4, v3, v[4:5]
	v_cmp_ne_u32_e32 vcc, v6, v4
	s_and_saveexec_b64 s[0:1], vcc
	s_xor_b64 s[6:7], exec, s[0:1]
	s_cbranch_execz .LBB0_1025
	s_add_i32 s86, s30, 0x900
	s_lshl_b64 s[0:1], s[86:87], 2
	s_add_u32 s10, s4, s0
	s_addc_u32 s11, s5, s1
	v_mov_b64_e32 v[4:5], s[10:11]
	flat_load_dword v2, v[4:5] sc1
	s_waitcnt vmcnt(0) lgkmcnt(0)
	v_cmp_eq_u32_e32 vcc, v2, v3
	s_and_saveexec_b64 s[8:9], vcc
	s_cbranch_execz .LBB0_1024
	s_mov_b32 s0, 1
	s_mov_b64 s[14:15], 0
	s_branch .LBB0_1016

.LBB0_1024:
	s_or_b64 exec, exec, s[8:9]
	s_waitcnt vmcnt(0) lgkmcnt(0)
	buffer_inv sc1
	s_waitcnt vmcnt(0)

.LBB0_1076:
	s_lshl_b32 s30, s40, 6
	s_add_i32 s86, s30, 0x500
	s_lshl_b64 s[0:1], s[86:87], 2
	s_add_u32 s0, s4, s0
	s_addc_u32 s1, s5, s1
	v_mov_b64_e32 v[6:7], s[0:1]
	flat_atomic_add v5, v[6:7], v1 sc0
	v_cvt_f32_u32_e32 v3, v4
	v_sub_u32_e32 v6, 0, v4
	v_rcp_iflag_f32_e32 v3, v3
	s_nop 0
	v_mul_f32_e32 v3, 0x4f7ffffe, v3
	v_cvt_u32_f32_e32 v3, v3
	v_mul_lo_u32 v6, v6, v3
	v_mul_hi_u32 v6, v3, v6
	v_add_u32_e32 v3, v3, v6
	s_waitcnt vmcnt(0) lgkmcnt(0)
	v_mul_hi_u32 v3, v5, v3
	v_mul_lo_u32 v6, v3, v4
	v_sub_u32_e32 v6, v5, v6
	v_cmp_ge_u32_e32 vcc, v6, v4
	v_add_u32_e32 v7, 1, v3
	s_nop 0
	v_cndmask_b32_e32 v3, v3, v7, vcc
	v_sub_u32_e32 v7, v6, v4
	v_cndmask_b32_e32 v6, v6, v7, vcc
	v_cmp_ge_u32_e32 vcc, v6, v4
	v_add_u32_e32 v6, 1, v3
	s_nop 0
	v_cndmask_b32_e32 v3, v3, v6, vcc
	v_add_u32_e32 v6, 1, v5
	v_mad_u64_u32 v[4:5], s[0:1], v4, v3, v[4:5]
	v_cmp_ne_u32_e32 vcc, v6, v4
	s_and_saveexec_b64 s[0:1], vcc
	s_xor_b64 s[6:7], exec, s[0:1]
	s_cbranch_execz .LBB0_1089
	s_add_i32 s86, s30, 0x900
	s_lshl_b64 s[0:1], s[86:87], 2
	s_add_u32 s10, s4, s0
	s_addc_u32 s11, s5, s1
	v_mov_b64_e32 v[4:5], s[10:11]
	flat_load_dword v2, v[4:5] sc1
	s_waitcnt vmcnt(0) lgkmcnt(0)
	v_cmp_eq_u32_e32 vcc, v2, v3
	s_and_saveexec_b64 s[8:9], vcc
	s_cbranch_execz .LBB0_1088
	s_mov_b32 s0, 1
	s_mov_b64 s[14:15], 0
	s_branch .LBB0_1080

.LBB0_1268:
	s_lshl_b32 s34, s49, 6
	s_add_i32 s86, s34, 0x500
	s_lshl_b64 s[0:1], s[86:87], 2
	s_add_u32 s0, s4, s0
	s_addc_u32 s1, s5, s1
	v_mov_b64_e32 v[6:7], s[0:1]
	flat_atomic_add v5, v[6:7], v1 sc0
	v_cvt_f32_u32_e32 v3, v4
	v_sub_u32_e32 v6, 0, v4
	v_rcp_iflag_f32_e32 v3, v3
	s_nop 0
	v_mul_f32_e32 v3, 0x4f7ffffe, v3
	v_cvt_u32_f32_e32 v3, v3
	v_mul_lo_u32 v6, v6, v3
	v_mul_hi_u32 v6, v3, v6
	v_add_u32_e32 v3, v3, v6
	s_waitcnt vmcnt(0) lgkmcnt(0)
	v_mul_hi_u32 v3, v5, v3
	v_mul_lo_u32 v6, v3, v4
	v_sub_u32_e32 v6, v5, v6
	v_cmp_ge_u32_e32 vcc, v6, v4
	v_add_u32_e32 v7, 1, v3
	s_nop 0
	v_cndmask_b32_e32 v3, v3, v7, vcc
	v_sub_u32_e32 v7, v6, v4
	v_cndmask_b32_e32 v6, v6, v7, vcc
	v_cmp_ge_u32_e32 vcc, v6, v4
	v_add_u32_e32 v6, 1, v3
	s_nop 0
	v_cndmask_b32_e32 v3, v3, v6, vcc
	v_add_u32_e32 v6, 1, v5
	v_mad_u64_u32 v[4:5], s[0:1], v4, v3, v[4:5]
	v_cmp_ne_u32_e32 vcc, v6, v4
	s_and_saveexec_b64 s[0:1], vcc
	s_xor_b64 s[8:9], exec, s[0:1]
	s_cbranch_execz .LBB0_1281
	s_add_i32 s86, s34, 0x900
	s_lshl_b64 s[0:1], s[86:87], 2
	s_add_u32 s14, s4, s0
	s_addc_u32 s15, s5, s1
	v_mov_b64_e32 v[4:5], s[14:15]
	flat_load_dword v2, v[4:5] sc1
	s_waitcnt vmcnt(0) lgkmcnt(0)
	v_cmp_eq_u32_e32 vcc, v2, v3
	s_and_saveexec_b64 s[10:11], vcc
	s_cbranch_execz .LBB0_1280
	s_mov_b32 s0, 1
	s_mov_b64 s[16:17], 0
	s_branch .LBB0_1272

.LBB0_1280:
	s_or_b64 exec, exec, s[10:11]
	s_waitcnt vmcnt(0) lgkmcnt(0)
	buffer_inv sc1
	s_waitcnt vmcnt(0)

.LBB0_1671:
	s_lshl_b32 s30, s49, 6
	s_add_i32 s86, s30, 0x500
	s_lshl_b64 s[0:1], s[86:87], 2
	s_add_u32 s0, s4, s0
	s_addc_u32 s1, s5, s1
	v_mov_b64_e32 v[6:7], s[0:1]
	flat_atomic_add v5, v[6:7], v1 sc0
	v_cvt_f32_u32_e32 v3, v4
	v_sub_u32_e32 v6, 0, v4
	v_rcp_iflag_f32_e32 v3, v3
	s_nop 0
	v_mul_f32_e32 v3, 0x4f7ffffe, v3
	v_cvt_u32_f32_e32 v3, v3
	v_mul_lo_u32 v6, v6, v3
	v_mul_hi_u32 v6, v3, v6
	v_add_u32_e32 v3, v3, v6
	s_waitcnt vmcnt(0) lgkmcnt(0)
	v_mul_hi_u32 v3, v5, v3
	v_mul_lo_u32 v6, v3, v4
	v_sub_u32_e32 v6, v5, v6
	v_cmp_ge_u32_e32 vcc, v6, v4
	v_add_u32_e32 v7, 1, v3
	s_nop 0
	v_cndmask_b32_e32 v3, v3, v7, vcc
	v_sub_u32_e32 v7, v6, v4
	v_cndmask_b32_e32 v6, v6, v7, vcc
	v_cmp_ge_u32_e32 vcc, v6, v4
	v_add_u32_e32 v6, 1, v3
	s_nop 0
	v_cndmask_b32_e32 v3, v3, v6, vcc
	v_add_u32_e32 v6, 1, v5
	v_mad_u64_u32 v[4:5], s[0:1], v4, v3, v[4:5]
	v_cmp_ne_u32_e32 vcc, v6, v4
	s_and_saveexec_b64 s[0:1], vcc
	s_xor_b64 s[2:3], exec, s[0:1]
	s_cbranch_execz .LBB0_1684
	s_add_i32 s86, s30, 0x900
	s_lshl_b64 s[0:1], s[86:87], 2
	s_add_u32 s10, s4, s0
	s_addc_u32 s11, s5, s1
	v_mov_b64_e32 v[4:5], s[10:11]
	flat_load_dword v2, v[4:5] sc1
	s_waitcnt vmcnt(0) lgkmcnt(0)
	v_cmp_eq_u32_e32 vcc, v2, v3
	s_and_saveexec_b64 s[8:9], vcc
	s_cbranch_execz .LBB0_1683
	s_mov_b32 s0, 1
	s_mov_b64 s[14:15], 0
	s_branch .LBB0_1675
